# loop-edge rotation: next step's address/slot/row-sum setup and loop-carried updates moved ahead of the step barrier
# speedup vs baseline: 1.0017x; 1.0017x over previous
.LBB5_820:
	v_lshlrev_b32_e32 v32, 1, v202
	v_and_b32_e32 v185, 32, v32
	v_lshlrev_b32_e32 v33, 8, v204
	s_movk_i32 s0, 0xc0
	v_add_u32_e32 v32, 0, v185
	v_and_or_b32 v187, v206, s0, v33
	v_add3_u32 v212, v32, v205, v187
	v_max3_f32 v32, v16, v17, v0
	v_max3_f32 v33, v18, v19, v1
	s_waitcnt vmcnt(0) lgkmcnt(0)
	s_barrier
	s_cmp_lg_u32 0, -1
	v_max3_f32 v32, v32, v2, v3
	v_max3_f32 v33, v33, v22, v23
	s_mov_b32 s48, 1
	v_max3_f32 v32, v32, v20, v21
	v_max3_f32 v33, v33, v6, v7
	s_mov_b32 s3, 0
	v_max3_f32 v32, v32, v4, v5
	v_max3_f32 v33, v33, v26, v27
	s_nop 0
	v_max3_f32 v32, v32, v24, v25
	v_max3_f32 v33, v33, v10, v11
	s_nop 0
	v_max3_f32 v32, v32, v8, v9
	v_max3_f32 v33, v33, v30, v31
	s_nop 0
	v_max3_f32 v32, v32, v28, v29
	v_max3_f32 v33, v33, v14, v15
	s_nop 0
	v_max3_f32 v32, v32, v12, v13
	s_nop 0
	v_max_f32_e32 v32, v32, v33
	s_nop 0
	v_mov_b32_e32 v33, v32
	s_nop 1
	v_permlane32_swap_b32_e32 v32, v33
	v_max_f32_e32 v32, v32, v33
	s_nop 0
	v_sub_f32_e32 v0, v0, v32
	v_sub_f32_e32 v1, v1, v32
	v_sub_f32_e32 v16, v16, v32
	v_sub_f32_e32 v17, v17, v32
	v_sub_f32_e32 v18, v18, v32
	v_sub_f32_e32 v2, v2, v32
	s_nop 0
	v_exp_f32_e32 v64, v0
	v_exp_f32_e32 v65, v1
	v_lshl_add_u64 v[0:1], v[188:189], 0, s[58:59]
	s_mov_b32 s0, m0
	s_mov_b32 m0, s64
	s_nop 0
	global_load_lds_dwordx4 v[0:1], off
	s_mov_b32 m0, s0
	s_cselect_b32 s0, 0, 0
	s_add_i32 s24, s0, s63
	v_lshl_add_u64 v[0:1], v[190:191], 0, s[82:83]
	s_add_i32 s0, s24, 0xa000
	s_mov_b32 s1, m0
	s_mov_b32 m0, s0
	s_nop 0
	global_load_lds_dwordx4 v[0:1], off
	s_mov_b32 m0, s1
	s_mov_b64 s[0:1], 0x20080
	v_lshl_add_u64 v[0:1], v[190:191], 0, s[0:1]
	s_add_i32 s24, s24, 0xc000
	s_mov_b32 s0, m0
	s_mov_b32 m0, s24
	s_nop 0
	global_load_lds_dwordx4 v[0:1], off
	s_mov_b32 m0, s0
	ds_read_b128 v[172:175], v208 offset:8192
	ds_read_b128 v[160:163], v208 offset:8704
	ds_read_b128 v[168:171], v208 offset:10240
	ds_read_b128 v[152:155], v208 offset:10752
	ds_read_b128 v[164:167], v208 offset:12288
	ds_read_b128 v[148:151], v208 offset:12800
	ds_read_b128 v[156:159], v208 offset:14336
	ds_read_b128 v[144:147], v208 offset:14848
	v_sub_f32_e32 v19, v19, v32
	v_sub_f32_e32 v3, v3, v32
	v_sub_f32_e32 v20, v20, v32
	v_sub_f32_e32 v4, v4, v32
	v_sub_f32_e32 v21, v21, v32
	v_sub_f32_e32 v5, v5, v32
	v_sub_f32_e32 v22, v22, v32
	v_sub_f32_e32 v6, v6, v32
	v_sub_f32_e32 v23, v23, v32
	v_sub_f32_e32 v7, v7, v32
	v_sub_f32_e32 v24, v24, v32
	v_sub_f32_e32 v8, v8, v32
	v_sub_f32_e32 v25, v25, v32
	v_sub_f32_e32 v9, v9, v32
	v_sub_f32_e32 v26, v26, v32
	v_sub_f32_e32 v10, v10, v32
	v_sub_f32_e32 v27, v27, v32
	v_sub_f32_e32 v11, v11, v32
	v_sub_f32_e32 v28, v28, v32
	v_sub_f32_e32 v12, v12, v32
	v_sub_f32_e32 v29, v29, v32
	v_sub_f32_e32 v13, v13, v32
	v_sub_f32_e32 v30, v30, v32
	v_sub_f32_e32 v14, v14, v32
	v_sub_f32_e32 v31, v31, v32
	v_sub_f32_e32 v15, v15, v32
	v_exp_f32_e32 v80, v16
	v_exp_f32_e32 v81, v17
	v_exp_f32_e32 v82, v18
	v_exp_f32_e32 v83, v19
	v_exp_f32_e32 v84, v20
	v_exp_f32_e32 v85, v21
	v_exp_f32_e32 v86, v22
	v_exp_f32_e32 v87, v23
	v_exp_f32_e32 v88, v24
	v_exp_f32_e32 v89, v25
	v_exp_f32_e32 v90, v26
	v_exp_f32_e32 v91, v27
	v_exp_f32_e32 v92, v28
	v_exp_f32_e32 v93, v29
	v_exp_f32_e32 v94, v30
	v_exp_f32_e32 v95, v31
	v_exp_f32_e32 v66, v2
	v_exp_f32_e32 v67, v3
	v_exp_f32_e32 v68, v4
	v_exp_f32_e32 v69, v5
	v_exp_f32_e32 v70, v6
	v_exp_f32_e32 v71, v7
	v_exp_f32_e32 v72, v8
	v_exp_f32_e32 v73, v9
	v_exp_f32_e32 v74, v10
	v_exp_f32_e32 v75, v11
	v_exp_f32_e32 v76, v12
	v_exp_f32_e32 v77, v13
	v_exp_f32_e32 v78, v14
	v_exp_f32_e32 v79, v15
	s_waitcnt vmcnt(3) lgkmcnt(0)
	s_barrier
	s_cmp_lt_i32 s17, 7
	v_cmp_gt_u32_e64 s[0:1], 32, v202
	v_add_f32_e32 v211, v179, v32
	s_cbranch_scc1 .LBB5_836
	v_mov_b32_e32 v16, v179
	v_mov_b32_e32 v17, v179
	v_mov_b32_e32 v30, v179
	v_mov_b32_e32 v31, v179
	s_mov_b64 s[12:13], 0xa0000
	v_mov_b32_e32 v18, v179
	v_mov_b32_e32 v19, v179
	v_mov_b32_e32 v20, v179
	v_mov_b32_e32 v21, v179
	v_mov_b32_e32 v22, v179
	v_mov_b32_e32 v23, v179
	v_mov_b32_e32 v24, v179
	v_mov_b32_e32 v25, v179
	v_mov_b32_e32 v26, v179
	v_mov_b32_e32 v27, v179
	v_mov_b32_e32 v28, v179
	v_mov_b32_e32 v29, v179
	v_mov_b64_e32 v[62:63], v[30:31]
	v_mov_b64_e32 v[46:47], v[30:31]
	v_mov_b64_e32 v[0:1], v[16:17]
	s_add_i32 s30, s17, -5
	v_lshl_add_u64 v[194:195], v[192:193], 0, s[58:59]
	v_lshl_add_u64 v[196:197], v[190:191], 0, s[58:59]
	v_lshl_add_u64 v[198:199], v[188:189], 0, s[12:13]
	s_mov_b32 s34, 0
	s_movk_i32 s3, 0x4000
	s_movk_i32 s33, 0x2000
	v_mov_b32_e32 v214, 0
	v_mov_b64_e32 v[60:61], v[28:29]
	v_mov_b64_e32 v[58:59], v[26:27]
	v_mov_b64_e32 v[56:57], v[24:25]
	v_mov_b64_e32 v[54:55], v[22:23]
	v_mov_b64_e32 v[52:53], v[20:21]
	v_mov_b64_e32 v[50:51], v[18:19]
	v_mov_b64_e32 v[48:49], v[16:17]
	v_mov_b64_e32 v[44:45], v[28:29]
	v_mov_b64_e32 v[42:43], v[26:27]
	v_mov_b64_e32 v[40:41], v[24:25]
	v_mov_b64_e32 v[38:39], v[22:23]
	v_mov_b64_e32 v[36:37], v[20:21]
	v_mov_b64_e32 v[34:35], v[18:19]
	v_mov_b64_e32 v[32:33], v[16:17]
	v_mov_b64_e32 v[2:3], v[18:19]
	v_mov_b64_e32 v[4:5], v[20:21]
	v_mov_b64_e32 v[6:7], v[22:23]
	v_mov_b64_e32 v[8:9], v[24:25]
	v_mov_b64_e32 v[10:11], v[26:27]
	v_mov_b64_e32 v[12:13], v[28:29]
	v_mov_b64_e32 v[14:15], v[30:31]
	s_mov_b32 s32, m0
	v_xor_b32_e32 v220, 0x80000000, v211
	v_mov_b32_e32 v221, v220
	v_mov_b32_e32 v222, v220
	v_mov_b32_e32 v223, v220
	v_mov_b32_e32 v224, v220
	v_mov_b32_e32 v225, v220
	v_mov_b32_e32 v226, v220
	v_mov_b32_e32 v227, v220
	v_mov_b32_e32 v228, v220
	v_mov_b32_e32 v229, v220
	v_mov_b32_e32 v230, v220
	v_mov_b32_e32 v231, v220
	v_mov_b32_e32 v232, v220
	v_mov_b32_e32 v233, v220
	v_mov_b32_e32 v234, v220
	v_mov_b32_e32 v235, v220
	v_add_u32_e32 v216, s80, v184
	s_lshl_b32 s99, s34, 1
	v_add_u32_e32 v183, s99, v212
	v_add_u32_e32 v215, s3, v208
	v_add_f32_e32 v251, v80, v81
	ds_read_b128 v[236:239], v207
	ds_read_b128 v[240:243], v207 offset:1024
	ds_read_b128 v[244:247], v207 offset:2048
	ds_read_b128 v[252:255], v207 offset:3072
	s_waitcnt lgkmcnt(0)
.LBB5_822:
	v_mfma_f32_32x32x16_bf16 v[112:127], v[172:175], v[236:239], v[220:235]
	s_add_i32 s24, s33, s64
	s_mov_b32 m0, s24
	v_lshl_add_u64 v[248:249], v[198:199], 0, s[36:37]
	global_load_lds_dwordx4 v[248:249], off
	v_add_f32_e32 v251, v82, v251
	v_add_f32_e32 v251, v83, v251
	v_add_f32_e32 v251, v84, v251
	v_add_f32_e32 v251, v85, v251
	v_cvt_pk_bf16_f32 v140, v80, v81
	v_cvt_pk_bf16_f32 v141, v82, v83
	ds_read_b128 v[172:175], v215
	v_mfma_f32_32x32x16_bf16 v[96:111], v[160:163], v[236:239], v[220:235]
	s_lshl_b32 s24, s3, 1
	s_add_i32 s24, s24, s66
	s_mov_b32 m0, s24
	v_lshl_add_u64 v[248:249], v[196:197], 0, s[36:37]
	global_load_lds_dwordx4 v[248:249], off
	v_add_f32_e32 v251, v86, v251
	v_add_f32_e32 v251, v87, v251
	v_add_f32_e32 v251, v88, v251
	v_add_f32_e32 v251, v89, v251
	v_cvt_pk_bf16_f32 v142, v84, v85
	v_cvt_pk_bf16_f32 v143, v86, v87
	ds_read_b128 v[160:163], v215 offset:512
	v_mfma_f32_32x32x16_bf16 v[112:127], v[168:171], v[240:243], v[112:127]
	s_addk_i32 s24, 0x2000
	s_mov_b32 m0, s24
	v_lshl_add_u64 v[248:249], v[194:195], 0, s[36:37]
	global_load_lds_dwordx4 v[248:249], off
	v_add_f32_e32 v251, v90, v251
	v_add_f32_e32 v251, v91, v251
	v_add_f32_e32 v251, v92, v251
	v_add_f32_e32 v251, v93, v251
	v_cvt_pk_bf16_f32 v136, v88, v89
	v_cvt_pk_bf16_f32 v137, v90, v91
	ds_read_b128 v[168:171], v215 offset:2048
	v_mfma_f32_32x32x16_bf16 v[96:111], v[152:155], v[240:243], v[96:111]
	v_add_f32_e32 v251, v94, v251
	v_add_f32_e32 v251, v95, v251
	v_add_f32_e32 v251, v64, v251
	v_add_f32_e32 v251, v65, v251
	v_cvt_pk_bf16_f32 v138, v92, v93
	v_cvt_pk_bf16_f32 v139, v94, v95
	ds_read_b128 v[152:155], v215 offset:2560
	v_mfma_f32_32x32x16_bf16 v[112:127], v[164:167], v[244:247], v[112:127]
	v_add_f32_e32 v251, v66, v251
	v_add_f32_e32 v251, v67, v251
	v_add_f32_e32 v251, v68, v251
	v_add_f32_e32 v251, v69, v251
	v_cvt_pk_bf16_f32 v132, v64, v65
	v_cvt_pk_bf16_f32 v133, v66, v67
	ds_read_b128 v[164:167], v215 offset:4096
	v_mfma_f32_32x32x16_bf16 v[96:111], v[148:151], v[244:247], v[96:111]
	v_add_f32_e32 v251, v70, v251
	v_add_f32_e32 v251, v71, v251
	v_add_f32_e32 v251, v72, v251
	v_add_f32_e32 v251, v73, v251
	v_cvt_pk_bf16_f32 v134, v68, v69
	v_cvt_pk_bf16_f32 v135, v70, v71
	ds_read_b128 v[148:151], v215 offset:4608
	v_mfma_f32_32x32x16_bf16 v[112:127], v[156:159], v[252:255], v[112:127]
	v_add_f32_e32 v251, v74, v251
	v_add_f32_e32 v251, v75, v251
	v_add_f32_e32 v251, v76, v251
	v_add_f32_e32 v251, v77, v251
	v_cvt_pk_bf16_f32 v128, v72, v73
	v_cvt_pk_bf16_f32 v129, v74, v75
	ds_read_b128 v[156:159], v215 offset:6144
	ds_read_b64_tr_b16 v[80:81], v183 offset:24576
	ds_read_b64_tr_b16 v[82:83], v183 offset:25088
	v_mfma_f32_32x32x16_bf16 v[96:111], v[144:147], v[252:255], v[96:111]
	v_add_f32_e32 v251, v78, v251
	v_add_f32_e32 v251, v79, v251
	v_cvt_pk_bf16_f32 v130, v76, v77
	v_cvt_pk_bf16_f32 v131, v78, v79
	ds_read_b128 v[144:147], v215 offset:6656
	ds_read_b64_tr_b16 v[84:85], v183 offset:28672
	ds_read_b64_tr_b16 v[86:87], v183 offset:29184
	s_waitcnt lgkmcnt(3)
	v_mfma_f32_32x32x16_bf16 v[16:31], v[140:143], v[80:83], v[16:31]
	ds_read_b64_tr_b16 v[88:89], v183 offset:32768
	ds_read_b64_tr_b16 v[90:91], v183 offset:33280
	v_max3_f32 v76, v112, v113, v114
	v_max3_f32 v76, v76, v115, v116
	v_max3_f32 v76, v76, v117, v118
	v_max3_f32 v76, v76, v119, v120
	v_max3_f32 v76, v76, v121, v122
	s_waitcnt lgkmcnt(2)
	v_mfma_f32_32x32x16_bf16 v[48:63], v[140:143], v[84:87], v[48:63]
	ds_read_b64_tr_b16 v[92:93], v183 offset:36864
	ds_read_b64_tr_b16 v[94:95], v183 offset:37376
	v_max3_f32 v76, v76, v123, v124
	v_max3_f32 v76, v76, v125, v126
	v_max3_f32 v76, v76, v127, v127
	v_max3_f32 v77, v96, v97, v98
	v_max3_f32 v77, v77, v99, v100
	s_waitcnt lgkmcnt(2)
	v_mfma_f32_32x32x16_bf16 v[32:47], v[140:143], v[88:91], v[32:47]
	ds_read_b64_tr_b16 v[64:65], v183 offset:25600
	ds_read_b64_tr_b16 v[66:67], v183 offset:26112
	v_max3_f32 v77, v77, v101, v102
	v_max3_f32 v77, v77, v103, v104
	v_max3_f32 v77, v77, v105, v106
	v_max3_f32 v77, v77, v107, v108
	s_waitcnt lgkmcnt(2)
	v_mfma_f32_32x32x16_bf16 v[0:15], v[140:143], v[92:95], v[0:15]
	ds_read_b64_tr_b16 v[68:69], v183 offset:29696
	ds_read_b64_tr_b16 v[70:71], v183 offset:30208
	v_max3_f32 v77, v77, v109, v110
	v_max3_f32 v77, v77, v111, v111
	v_max_f32_e32 v76, v76, v77
	v_mov_b32_e32 v77, v76
	s_waitcnt lgkmcnt(2)
	v_mfma_f32_32x32x16_bf16 v[16:31], v[136:139], v[64:67], v[16:31]
	ds_read_b64_tr_b16 v[80:81], v183 offset:33792
	ds_read_b64_tr_b16 v[82:83], v183 offset:34304
	v_permlane32_swap_b32_e32 v76, v77
	v_max_f32_e32 v77, v77, v77
	v_max_f32_e32 v76, v76, v76
	v_max_f32_e32 v76, v76, v77
	v_cmp_lt_f32_e32 vcc, s85, v76
	s_cmp_lg_u64 vcc, 0
	v_add_f32_e32 v214, v214, v251
	s_cselect_b64 s[46:47], -1, 0
	s_cbranch_vccnz .LBB5_830
.LBB5_823:
	s_waitcnt lgkmcnt(2)
	v_mfma_f32_32x32x16_bf16 v[48:63], v[136:139], v[68:71], v[48:63]
	ds_read_b64_tr_b16 v[84:85], v183 offset:37888
	ds_read_b64_tr_b16 v[86:87], v183 offset:38400
	v_exp_f32_e32 v112, v112
	v_exp_f32_e32 v113, v113
	v_exp_f32_e32 v114, v114
	s_waitcnt lgkmcnt(2)
	v_mfma_f32_32x32x16_bf16 v[32:47], v[136:139], v[80:83], v[32:47]
	ds_read_b64_tr_b16 v[88:89], v183 offset:26624
	ds_read_b64_tr_b16 v[90:91], v183 offset:27136
	v_exp_f32_e32 v115, v115
	v_exp_f32_e32 v116, v116
	v_exp_f32_e32 v117, v117
	s_waitcnt lgkmcnt(2)
	v_mfma_f32_32x32x16_bf16 v[0:15], v[136:139], v[84:87], v[0:15]
	ds_read_b64_tr_b16 v[92:93], v183 offset:30720
	ds_read_b64_tr_b16 v[94:95], v183 offset:31232
	v_exp_f32_e32 v118, v118
	v_exp_f32_e32 v119, v119
	v_exp_f32_e32 v120, v120
	s_waitcnt lgkmcnt(2)
	v_mfma_f32_32x32x16_bf16 v[16:31], v[132:135], v[88:91], v[16:31]
	ds_read_b64_tr_b16 v[64:65], v183 offset:34816
	ds_read_b64_tr_b16 v[66:67], v183 offset:35328
	v_exp_f32_e32 v121, v121
	v_exp_f32_e32 v122, v122
	v_exp_f32_e32 v123, v123
	s_waitcnt lgkmcnt(2)
	v_mfma_f32_32x32x16_bf16 v[48:63], v[132:135], v[92:95], v[48:63]
	ds_read_b64_tr_b16 v[68:69], v183 offset:38912
	ds_read_b64_tr_b16 v[70:71], v183 offset:39424
	v_exp_f32_e32 v124, v124
	v_exp_f32_e32 v125, v125
	v_exp_f32_e32 v126, v126
	s_waitcnt lgkmcnt(2)
	v_mfma_f32_32x32x16_bf16 v[32:47], v[132:135], v[64:67], v[32:47]
	ds_read_b64_tr_b16 v[80:81], v183 offset:27648
	ds_read_b64_tr_b16 v[82:83], v183 offset:28160
	v_exp_f32_e32 v127, v127
	v_exp_f32_e32 v96, v96
	v_exp_f32_e32 v97, v97
	s_waitcnt lgkmcnt(2)
	v_mfma_f32_32x32x16_bf16 v[0:15], v[132:135], v[68:71], v[0:15]
	ds_read_b64_tr_b16 v[84:85], v183 offset:31744
	ds_read_b64_tr_b16 v[86:87], v183 offset:32256
	v_exp_f32_e32 v98, v98
	v_exp_f32_e32 v99, v99
	v_exp_f32_e32 v100, v100
	s_waitcnt lgkmcnt(2)
	v_mfma_f32_32x32x16_bf16 v[16:31], v[128:131], v[80:83], v[16:31]
	ds_read_b64_tr_b16 v[88:89], v183 offset:35840
	ds_read_b64_tr_b16 v[90:91], v183 offset:36352
	v_exp_f32_e32 v101, v101
	v_exp_f32_e32 v102, v102
	v_exp_f32_e32 v103, v103
	s_waitcnt lgkmcnt(2)
	v_mfma_f32_32x32x16_bf16 v[48:63], v[128:131], v[84:87], v[48:63]
	ds_read_b64_tr_b16 v[92:93], v183 offset:39936
	ds_read_b64_tr_b16 v[94:95], v183 offset:40448
	v_exp_f32_e32 v104, v104
	v_exp_f32_e32 v105, v105
	v_exp_f32_e32 v106, v106
	s_waitcnt lgkmcnt(2)
	v_mfma_f32_32x32x16_bf16 v[32:47], v[128:131], v[88:91], v[32:47]
	v_exp_f32_e32 v107, v107
	v_exp_f32_e32 v108, v108
	v_exp_f32_e32 v109, v109
	s_waitcnt lgkmcnt(0)
	v_mfma_f32_32x32x16_bf16 v[0:15], v[128:131], v[92:95], v[0:15]
	v_exp_f32_e32 v110, v110
	v_exp_f32_e32 v111, v111
	s_add_i32 s24, s3, 0x2000
	s_cmpk_lg_i32 s3, 0x4000
	s_cselect_b32 s25, s24, 0
	s_lshl_b32 s24, s33, 1
	v_add_u32_e32 v213, s24, v212
	v_add_u32_e32 v215, s25, v208
	v_add_f32_e32 v251, v112, v113
	s_waitcnt vmcnt(3) lgkmcnt(0)
	s_barrier
	s_andn2_b64 vcc, exec, s[46:47]
	s_cbranch_vccnz .LBB5_825
	s_waitcnt lgkmcnt(0)
	ds_read_b128 v[72:75], v216 offset:96
	ds_read_b128 v[76:79], v216 offset:64
	ds_read_b128 v[80:83], v216 offset:32
	ds_read_b128 v[84:87], v216
	s_waitcnt lgkmcnt(3)
	v_pk_mul_f32 v[28:29], v[28:29], v[72:73]
	s_waitcnt lgkmcnt(2)
	v_pk_mul_f32 v[24:25], v[24:25], v[76:77]
	s_waitcnt lgkmcnt(1)
	v_pk_mul_f32 v[20:21], v[20:21], v[80:81]
	v_pk_mul_f32 v[30:31], v[30:31], v[74:75]
	v_pk_mul_f32 v[26:27], v[26:27], v[78:79]
	v_pk_mul_f32 v[22:23], v[22:23], v[82:83]
	s_waitcnt lgkmcnt(0)
	v_pk_mul_f32 v[18:19], v[18:19], v[86:87]
	v_pk_mul_f32 v[16:17], v[16:17], v[84:85]
	v_pk_mul_f32 v[60:61], v[60:61], v[72:73]
	v_pk_mul_f32 v[56:57], v[56:57], v[76:77]
	v_pk_mul_f32 v[52:53], v[52:53], v[80:81]
	v_pk_mul_f32 v[62:63], v[62:63], v[74:75]
	v_pk_mul_f32 v[58:59], v[58:59], v[78:79]
	v_pk_mul_f32 v[54:55], v[54:55], v[82:83]
	v_pk_mul_f32 v[50:51], v[50:51], v[86:87]
	v_pk_mul_f32 v[48:49], v[48:49], v[84:85]
	v_pk_mul_f32 v[44:45], v[44:45], v[72:73]
	v_pk_mul_f32 v[40:41], v[40:41], v[76:77]
	v_pk_mul_f32 v[36:37], v[36:37], v[80:81]
	v_pk_mul_f32 v[46:47], v[46:47], v[74:75]
	v_pk_mul_f32 v[42:43], v[42:43], v[78:79]
	v_pk_mul_f32 v[38:39], v[38:39], v[82:83]
	v_pk_mul_f32 v[34:35], v[34:35], v[86:87]
	v_pk_mul_f32 v[32:33], v[32:33], v[84:85]
	v_pk_mul_f32 v[12:13], v[12:13], v[72:73]
	v_pk_mul_f32 v[8:9], v[8:9], v[76:77]
	v_pk_mul_f32 v[4:5], v[4:5], v[80:81]
	v_pk_mul_f32 v[14:15], v[14:15], v[74:75]
	v_pk_mul_f32 v[10:11], v[10:11], v[78:79]
	v_pk_mul_f32 v[6:7], v[6:7], v[82:83]
	v_pk_mul_f32 v[2:3], v[2:3], v[86:87]
	v_pk_mul_f32 v[0:1], v[0:1], v[84:85]
.LBB5_825:
	v_mfma_f32_32x32x16_bf16 v[80:95], v[172:175], v[236:239], v[220:235]
	s_add_i32 s24, s3, s64
	s_mov_b32 m0, s24
	v_add_f32_e32 v251, v114, v251
	global_load_lds_dwordx4 v[198:199], off
	v_add_f32_e32 v251, v115, v251
	v_add_f32_e32 v251, v116, v251
	v_add_f32_e32 v251, v117, v251
	v_cvt_pk_bf16_f32 v140, v112, v113
	v_cvt_pk_bf16_f32 v141, v114, v115
	ds_read_b128 v[172:175], v215
	v_mfma_f32_32x32x16_bf16 v[64:79], v[160:163], v[236:239], v[220:235]
	s_lshl_b32 s24, s25, 1
	s_add_i32 s24, s24, s66
	s_mov_b32 m0, s24
	v_add_f32_e32 v251, v118, v251
	global_load_lds_dwordx4 v[196:197], off
	v_add_f32_e32 v251, v119, v251
	v_add_f32_e32 v251, v120, v251
	v_add_f32_e32 v251, v121, v251
	v_cvt_pk_bf16_f32 v142, v116, v117
	v_cvt_pk_bf16_f32 v143, v118, v119
	ds_read_b128 v[160:163], v215 offset:512
	v_mfma_f32_32x32x16_bf16 v[80:95], v[168:171], v[240:243], v[80:95]
	s_addk_i32 s24, 0x2000
	s_mov_b32 m0, s24
	v_add_f32_e32 v251, v122, v251
	global_load_lds_dwordx4 v[194:195], off
	v_add_f32_e32 v251, v123, v251
	v_add_f32_e32 v251, v124, v251
	v_add_f32_e32 v251, v125, v251
	v_cvt_pk_bf16_f32 v136, v120, v121
	v_cvt_pk_bf16_f32 v137, v122, v123
	ds_read_b128 v[168:171], v215 offset:2048
	v_mfma_f32_32x32x16_bf16 v[64:79], v[152:155], v[240:243], v[64:79]
	v_add_f32_e32 v251, v126, v251
	v_add_f32_e32 v251, v127, v251
	v_add_f32_e32 v251, v96, v251
	v_add_f32_e32 v251, v97, v251
	v_cvt_pk_bf16_f32 v138, v124, v125
	v_cvt_pk_bf16_f32 v139, v126, v127
	ds_read_b128 v[152:155], v215 offset:2560
	v_mfma_f32_32x32x16_bf16 v[80:95], v[164:167], v[244:247], v[80:95]
	v_add_f32_e32 v251, v98, v251
	v_add_f32_e32 v251, v99, v251
	v_add_f32_e32 v251, v100, v251
	v_add_f32_e32 v251, v101, v251
	v_cvt_pk_bf16_f32 v132, v96, v97
	v_cvt_pk_bf16_f32 v133, v98, v99
	ds_read_b128 v[164:167], v215 offset:4096
	v_mfma_f32_32x32x16_bf16 v[64:79], v[148:151], v[244:247], v[64:79]
	v_add_f32_e32 v251, v102, v251
	v_add_f32_e32 v251, v103, v251
	v_add_f32_e32 v251, v104, v251
	v_add_f32_e32 v251, v105, v251
	v_cvt_pk_bf16_f32 v134, v100, v101
	v_cvt_pk_bf16_f32 v135, v102, v103
	ds_read_b128 v[148:151], v215 offset:4608
	v_mfma_f32_32x32x16_bf16 v[80:95], v[156:159], v[252:255], v[80:95]
	v_add_f32_e32 v251, v106, v251
	v_add_f32_e32 v251, v107, v251
	v_add_f32_e32 v251, v108, v251
	v_add_f32_e32 v251, v109, v251
	v_cvt_pk_bf16_f32 v128, v104, v105
	v_cvt_pk_bf16_f32 v129, v106, v107
	ds_read_b128 v[156:159], v215 offset:6144
	ds_read_b64_tr_b16 v[112:113], v213 offset:24576
	ds_read_b64_tr_b16 v[114:115], v213 offset:25088
	v_mfma_f32_32x32x16_bf16 v[64:79], v[144:147], v[252:255], v[64:79]
	v_add_f32_e32 v251, v110, v251
	v_add_f32_e32 v251, v111, v251
	v_cvt_pk_bf16_f32 v130, v108, v109
	v_cvt_pk_bf16_f32 v131, v110, v111
	ds_read_b128 v[144:147], v215 offset:6656
	ds_read_b64_tr_b16 v[116:117], v213 offset:28672
	ds_read_b64_tr_b16 v[118:119], v213 offset:29184
	s_waitcnt lgkmcnt(3)
	v_mfma_f32_32x32x16_bf16 v[16:31], v[140:143], v[112:115], v[16:31]
	ds_read_b64_tr_b16 v[120:121], v213 offset:32768
	ds_read_b64_tr_b16 v[122:123], v213 offset:33280
	v_max3_f32 v108, v80, v81, v82
	v_max3_f32 v108, v108, v83, v84
	v_max3_f32 v108, v108, v85, v86
	v_max3_f32 v108, v108, v87, v88
	v_max3_f32 v108, v108, v89, v90
	s_waitcnt lgkmcnt(2)
	v_mfma_f32_32x32x16_bf16 v[48:63], v[140:143], v[116:119], v[48:63]
	ds_read_b64_tr_b16 v[124:125], v213 offset:36864
	ds_read_b64_tr_b16 v[126:127], v213 offset:37376
	v_max3_f32 v108, v108, v91, v92
	v_max3_f32 v108, v108, v93, v94
	v_max3_f32 v108, v108, v95, v95
	v_max3_f32 v109, v64, v65, v66
	v_max3_f32 v109, v109, v67, v68
	s_waitcnt lgkmcnt(2)
	v_mfma_f32_32x32x16_bf16 v[32:47], v[140:143], v[120:123], v[32:47]
	ds_read_b64_tr_b16 v[96:97], v213 offset:25600
	ds_read_b64_tr_b16 v[98:99], v213 offset:26112
	v_max3_f32 v109, v109, v69, v70
	v_max3_f32 v109, v109, v71, v72
	v_max3_f32 v109, v109, v73, v74
	v_max3_f32 v109, v109, v75, v76
	s_waitcnt lgkmcnt(2)
	v_mfma_f32_32x32x16_bf16 v[0:15], v[140:143], v[124:127], v[0:15]
	ds_read_b64_tr_b16 v[100:101], v213 offset:29696
	ds_read_b64_tr_b16 v[102:103], v213 offset:30208
	v_max3_f32 v109, v109, v77, v78
	v_max3_f32 v109, v109, v79, v79
	v_max_f32_e32 v108, v108, v109
	v_mov_b32_e32 v109, v108
	s_waitcnt lgkmcnt(2)
	v_mfma_f32_32x32x16_bf16 v[16:31], v[136:139], v[96:99], v[16:31]
	ds_read_b64_tr_b16 v[112:113], v213 offset:33792
	ds_read_b64_tr_b16 v[114:115], v213 offset:34304
	v_permlane32_swap_b32_e32 v108, v109
	v_max_f32_e32 v109, v109, v109
	v_max_f32_e32 v108, v108, v108
	v_max_f32_e32 v108, v108, v109
	v_cmp_lt_f32_e32 vcc, s85, v108
	s_cmp_lg_u64 vcc, 0
	v_add_f32_e32 v214, v214, v251
	s_cselect_b64 s[46:47], -1, 0
	s_cbranch_vccnz .LBB5_833
.LBB5_826:
	s_waitcnt lgkmcnt(2)
	v_mfma_f32_32x32x16_bf16 v[48:63], v[136:139], v[100:103], v[48:63]
	ds_read_b64_tr_b16 v[116:117], v213 offset:37888
	ds_read_b64_tr_b16 v[118:119], v213 offset:38400
	v_exp_f32_e32 v80, v80
	v_exp_f32_e32 v81, v81
	v_exp_f32_e32 v82, v82
	s_waitcnt lgkmcnt(2)
	v_mfma_f32_32x32x16_bf16 v[32:47], v[136:139], v[112:115], v[32:47]
	ds_read_b64_tr_b16 v[120:121], v213 offset:26624
	ds_read_b64_tr_b16 v[122:123], v213 offset:27136
	v_exp_f32_e32 v83, v83
	v_exp_f32_e32 v84, v84
	v_exp_f32_e32 v85, v85
	s_waitcnt lgkmcnt(2)
	v_mfma_f32_32x32x16_bf16 v[0:15], v[136:139], v[116:119], v[0:15]
	ds_read_b64_tr_b16 v[124:125], v213 offset:30720
	ds_read_b64_tr_b16 v[126:127], v213 offset:31232
	v_exp_f32_e32 v86, v86
	v_exp_f32_e32 v87, v87
	v_exp_f32_e32 v88, v88
	s_waitcnt lgkmcnt(2)
	v_mfma_f32_32x32x16_bf16 v[16:31], v[132:135], v[120:123], v[16:31]
	ds_read_b64_tr_b16 v[96:97], v213 offset:34816
	ds_read_b64_tr_b16 v[98:99], v213 offset:35328
	v_exp_f32_e32 v89, v89
	v_exp_f32_e32 v90, v90
	v_exp_f32_e32 v91, v91
	s_waitcnt lgkmcnt(2)
	v_mfma_f32_32x32x16_bf16 v[48:63], v[132:135], v[124:127], v[48:63]
	ds_read_b64_tr_b16 v[100:101], v213 offset:38912
	ds_read_b64_tr_b16 v[102:103], v213 offset:39424
	v_exp_f32_e32 v92, v92
	v_exp_f32_e32 v93, v93
	v_exp_f32_e32 v94, v94
	s_waitcnt lgkmcnt(2)
	v_mfma_f32_32x32x16_bf16 v[32:47], v[132:135], v[96:99], v[32:47]
	ds_read_b64_tr_b16 v[112:113], v213 offset:27648
	ds_read_b64_tr_b16 v[114:115], v213 offset:28160
	v_exp_f32_e32 v95, v95
	v_exp_f32_e32 v64, v64
	v_exp_f32_e32 v65, v65
	s_waitcnt lgkmcnt(2)
	v_mfma_f32_32x32x16_bf16 v[0:15], v[132:135], v[100:103], v[0:15]
	ds_read_b64_tr_b16 v[116:117], v213 offset:31744
	ds_read_b64_tr_b16 v[118:119], v213 offset:32256
	v_exp_f32_e32 v66, v66
	v_exp_f32_e32 v67, v67
	v_exp_f32_e32 v68, v68
	s_waitcnt lgkmcnt(2)
	v_mfma_f32_32x32x16_bf16 v[16:31], v[128:131], v[112:115], v[16:31]
	ds_read_b64_tr_b16 v[120:121], v213 offset:35840
	ds_read_b64_tr_b16 v[122:123], v213 offset:36352
	v_exp_f32_e32 v69, v69
	v_exp_f32_e32 v70, v70
	v_exp_f32_e32 v71, v71
	s_waitcnt lgkmcnt(2)
	v_mfma_f32_32x32x16_bf16 v[48:63], v[128:131], v[116:119], v[48:63]
	ds_read_b64_tr_b16 v[124:125], v213 offset:39936
	ds_read_b64_tr_b16 v[126:127], v213 offset:40448
	v_exp_f32_e32 v72, v72
	v_exp_f32_e32 v73, v73
	v_exp_f32_e32 v74, v74
	s_waitcnt lgkmcnt(2)
	v_mfma_f32_32x32x16_bf16 v[32:47], v[128:131], v[120:123], v[32:47]
	v_exp_f32_e32 v75, v75
	v_exp_f32_e32 v76, v76
	v_exp_f32_e32 v77, v77
	s_waitcnt lgkmcnt(0)
	v_mfma_f32_32x32x16_bf16 v[0:15], v[128:131], v[124:127], v[0:15]
	v_exp_f32_e32 v78, v78
	v_exp_f32_e32 v79, v79
	s_add_i32 s48, s48, 2
	s_add_i32 s24, s25, 0x2000
	s_cmpk_lg_i32 s25, 0x4000
	s_cselect_b32 s24, s24, 0
	v_lshl_add_u64 v[194:195], v[194:195], 0, s[28:29]
	v_lshl_add_u64 v[196:197], v[196:197], 0, s[28:29]
	v_lshl_add_u64 v[198:199], v[198:199], 0, s[28:29]
	s_lshl_b32 s99, s3, 1
	v_add_u32_e32 v183, s99, v212
	v_add_u32_e32 v215, s24, v208
	v_add_f32_e32 v251, v80, v81
	s_mov_b32 m0, s32
	s_waitcnt vmcnt(3) lgkmcnt(0)
	s_barrier
	s_andn2_b64 vcc, exec, s[46:47]
	s_cbranch_vccnz .LBB5_828
	s_waitcnt lgkmcnt(0)
	ds_read_b128 v[96:99], v216 offset:96
	ds_read_b128 v[100:103], v216 offset:64
	ds_read_b128 v[104:107], v216 offset:32
	ds_read_b128 v[108:111], v216
	s_waitcnt lgkmcnt(3)
	v_pk_mul_f32 v[28:29], v[28:29], v[96:97]
	s_waitcnt lgkmcnt(2)
	v_pk_mul_f32 v[24:25], v[24:25], v[100:101]
	s_waitcnt lgkmcnt(1)
	v_pk_mul_f32 v[20:21], v[20:21], v[104:105]
	v_pk_mul_f32 v[30:31], v[30:31], v[98:99]
	v_pk_mul_f32 v[26:27], v[26:27], v[102:103]
	v_pk_mul_f32 v[22:23], v[22:23], v[106:107]
	s_waitcnt lgkmcnt(0)
	v_pk_mul_f32 v[18:19], v[18:19], v[110:111]
	v_pk_mul_f32 v[16:17], v[16:17], v[108:109]
	v_pk_mul_f32 v[60:61], v[60:61], v[96:97]
	v_pk_mul_f32 v[56:57], v[56:57], v[100:101]
	v_pk_mul_f32 v[52:53], v[52:53], v[104:105]
	v_pk_mul_f32 v[62:63], v[62:63], v[98:99]
	v_pk_mul_f32 v[58:59], v[58:59], v[102:103]
	v_pk_mul_f32 v[54:55], v[54:55], v[106:107]
	v_pk_mul_f32 v[50:51], v[50:51], v[110:111]
	v_pk_mul_f32 v[48:49], v[48:49], v[108:109]
	v_pk_mul_f32 v[44:45], v[44:45], v[96:97]
	v_pk_mul_f32 v[40:41], v[40:41], v[100:101]
	v_pk_mul_f32 v[36:37], v[36:37], v[104:105]
	v_pk_mul_f32 v[46:47], v[46:47], v[98:99]
	v_pk_mul_f32 v[42:43], v[42:43], v[102:103]
	v_pk_mul_f32 v[38:39], v[38:39], v[106:107]
	v_pk_mul_f32 v[34:35], v[34:35], v[110:111]
	v_pk_mul_f32 v[32:33], v[32:33], v[108:109]
	v_pk_mul_f32 v[12:13], v[12:13], v[96:97]
	v_pk_mul_f32 v[8:9], v[8:9], v[100:101]
	v_pk_mul_f32 v[4:5], v[4:5], v[104:105]
	v_pk_mul_f32 v[14:15], v[14:15], v[98:99]
	v_pk_mul_f32 v[10:11], v[10:11], v[102:103]
	v_pk_mul_f32 v[6:7], v[6:7], v[106:107]
	v_pk_mul_f32 v[2:3], v[2:3], v[110:111]
	v_pk_mul_f32 v[0:1], v[0:1], v[108:109]
.LBB5_828:
	s_cmp_ge_i32 s48, s30
	s_cbranch_scc1 .LBB5_837
	s_mov_b32 s34, s3
	s_mov_b32 s33, s25
	s_mov_b32 s3, s24
	s_branch .LBB5_822

	.amdhsa_kernel _Z4mega4Args
		.amdhsa_group_segment_fixed_size 0
		.amdhsa_private_segment_fixed_size 0
		.amdhsa_kernarg_size 480
		.amdhsa_user_sgpr_count 2
		.amdhsa_user_sgpr_dispatch_ptr 0
		.amdhsa_user_sgpr_queue_ptr 0
		.amdhsa_user_sgpr_kernarg_segment_ptr 1
		.amdhsa_user_sgpr_dispatch_id 0
		.amdhsa_user_sgpr_kernarg_preload_length 0
		.amdhsa_user_sgpr_kernarg_preload_offset 0
		.amdhsa_user_sgpr_private_segment_size 0
		.amdhsa_uses_dynamic_stack 0
		.amdhsa_enable_private_segment 0
		.amdhsa_system_sgpr_workgroup_id_x 1
		.amdhsa_system_sgpr_workgroup_id_y 0
		.amdhsa_system_sgpr_workgroup_id_z 0
		.amdhsa_system_sgpr_workgroup_info 0
		.amdhsa_system_vgpr_workitem_id 2
		.amdhsa_next_free_vgpr 256
		.amdhsa_next_free_sgpr 100
		.amdhsa_accum_offset 256
		.amdhsa_reserve_vcc 1
		.amdhsa_float_round_mode_32 0
		.amdhsa_float_round_mode_16_64 0
		.amdhsa_float_denorm_mode_32 3
		.amdhsa_float_denorm_mode_16_64 3
		.amdhsa_dx10_clamp 1
		.amdhsa_ieee_mode 1
		.amdhsa_fp16_overflow 0
		.amdhsa_tg_split 0
		.amdhsa_exception_fp_ieee_invalid_op 0
		.amdhsa_exception_fp_denorm_src 0
		.amdhsa_exception_fp_ieee_div_zero 0
		.amdhsa_exception_fp_ieee_overflow 0
		.amdhsa_exception_fp_ieee_underflow 0
		.amdhsa_exception_fp_ieee_inexact 0
		.amdhsa_exception_int_div_zero 0
	.end_amdhsa_kernel

amdhsa.kernels:
  - .agpr_count:     0
    .args:
      - .address_space:  global
        .offset:         0
        .size:           8
        .value_kind:     global_buffer
      - .address_space:  global
        .offset:         8
        .size:           8
        .value_kind:     global_buffer
      - .offset:         16
        .size:           4
        .value_kind:     by_value
      - .offset:         20
        .size:           4
        .value_kind:     by_value
      - .offset:         24
        .size:           80
        .value_kind:     by_value
    .group_segment_fixed_size: 16640
    .kernarg_segment_align: 8
    .kernarg_segment_size: 104
    .language:       OpenCL C
    .language_version:
      - 2
      - 0
    .max_flat_workgroup_size: 256
    .name:           _Z9dumb_gemmPKtS0_ii7DumbEpi
    .private_segment_fixed_size: 0
    .sgpr_count:     35
    .sgpr_spill_count: 0
    .symbol:         _Z9dumb_gemmPKtS0_ii7DumbEpi.kd
    .uniform_work_group_size: 1
    .uses_dynamic_stack: false
    .vgpr_count:     52
    .vgpr_spill_count: 0
    .wavefront_size: 64
  - .agpr_count:     0
    .args:
      - .address_space:  global
        .offset:         0
        .size:           8
        .value_kind:     global_buffer
      - .address_space:  global
        .offset:         8
        .size:           8
        .value_kind:     global_buffer
    .group_segment_fixed_size: 0
    .kernarg_segment_align: 8
    .kernarg_segment_size: 16
    .language:       OpenCL C
    .language_version:
      - 2
      - 0
    .max_flat_workgroup_size: 256
    .name:           _Z10dumb_rowssPKfPf
    .private_segment_fixed_size: 0
    .sgpr_count:     14
    .sgpr_spill_count: 0
    .symbol:         _Z10dumb_rowssPKfPf.kd
    .uniform_work_group_size: 1
    .uses_dynamic_stack: false
    .vgpr_count:     8
    .vgpr_spill_count: 0
    .wavefront_size: 64
  - .agpr_count:     0
    .args:
      - .address_space:  global
        .offset:         0
        .size:           8
        .value_kind:     global_buffer
      - .address_space:  global
        .offset:         8
        .size:           8
        .value_kind:     global_buffer
      - .address_space:  global
        .offset:         16
        .size:           8
        .value_kind:     global_buffer
    .group_segment_fixed_size: 0
    .kernarg_segment_align: 8
    .kernarg_segment_size: 24
    .language:       OpenCL C
    .language_version:
      - 2
      - 0
    .max_flat_workgroup_size: 256
    .name:           _Z9dumb_ropePtPKfS1_
    .private_segment_fixed_size: 0
    .sgpr_count:     16
    .sgpr_spill_count: 0
    .symbol:         _Z9dumb_ropePtPKfS1_.kd
    .uniform_work_group_size: 1
    .uses_dynamic_stack: false
    .vgpr_count:     8
    .vgpr_spill_count: 0
    .wavefront_size: 64
  - .agpr_count:     0
    .args:
      - .address_space:  global
        .offset:         0
        .size:           8
        .value_kind:     global_buffer
      - .address_space:  global
        .offset:         8
        .size:           8
        .value_kind:     global_buffer
      - .address_space:  global
        .offset:         16
        .size:           8
        .value_kind:     global_buffer
      - .address_space:  global
        .offset:         24
        .size:           8
        .value_kind:     global_buffer
      - .address_space:  global
        .offset:         32
        .size:           8
        .value_kind:     global_buffer
      - .address_space:  global
        .offset:         40
        .size:           8
        .value_kind:     global_buffer
      - .address_space:  global
        .offset:         48
        .size:           8
        .value_kind:     global_buffer
      - .address_space:  global
        .offset:         56
        .size:           8
        .value_kind:     global_buffer
      - .address_space:  global
        .offset:         64
        .size:           8
        .value_kind:     global_buffer
      - .address_space:  global
        .offset:         72
        .size:           8
        .value_kind:     global_buffer
    .group_segment_fixed_size: 0
    .kernarg_segment_align: 8
    .kernarg_segment_size: 80
    .language:       OpenCL C
    .language_version:
      - 2
      - 0
    .max_flat_workgroup_size: 64
    .name:           _Z8dumb_ssmPKtPtPKfS3_S3_S3_S3_S3_S3_S3_
    .private_segment_fixed_size: 0
    .sgpr_count:     60
    .sgpr_spill_count: 0
    .symbol:         _Z8dumb_ssmPKtPtPKfS3_S3_S3_S3_S3_S3_S3_.kd
    .uniform_work_group_size: 1
    .uses_dynamic_stack: false
    .vgpr_count:     120
    .vgpr_spill_count: 0
    .wavefront_size: 64
  - .agpr_count:     0
    .args:
      - .address_space:  global
        .offset:         0
        .size:           8
        .value_kind:     global_buffer
      - .address_space:  global
        .offset:         8
        .size:           8
        .value_kind:     global_buffer
      - .address_space:  global
        .offset:         16
        .size:           8
        .value_kind:     global_buffer
      - .address_space:  global
        .offset:         24
        .size:           8
        .value_kind:     global_buffer
      - .address_space:  global
        .offset:         32
        .size:           8
        .value_kind:     global_buffer
    .group_segment_fixed_size: 33032
    .kernarg_segment_align: 8
    .kernarg_segment_size: 40
    .language:       OpenCL C
    .language_version:
      - 2
      - 0
    .max_flat_workgroup_size: 128
    .name:           _Z9dumb_attnPKtS0_S0_PtS1_
    .private_segment_fixed_size: 0
    .sgpr_count:     28
    .sgpr_spill_count: 0
    .symbol:         _Z9dumb_attnPKtS0_S0_PtS1_.kd
    .uniform_work_group_size: 1
    .uses_dynamic_stack: false
    .vgpr_count:     137
    .vgpr_spill_count: 0
    .wavefront_size: 64
  - .agpr_count:     0
    .args:
      - .offset:         0
        .size:           224
        .value_kind:     by_value
      - .offset:         224
        .size:           4
        .value_kind:     hidden_block_count_x
      - .offset:         228
        .size:           4
        .value_kind:     hidden_block_count_y
      - .offset:         232
        .size:           4
        .value_kind:     hidden_block_count_z
      - .offset:         236
        .size:           2
        .value_kind:     hidden_group_size_x
      - .offset:         238
        .size:           2
        .value_kind:     hidden_group_size_y
      - .offset:         240
        .size:           2
        .value_kind:     hidden_group_size_z
      - .offset:         242
        .size:           2
        .value_kind:     hidden_remainder_x
      - .offset:         244
        .size:           2
        .value_kind:     hidden_remainder_y
      - .offset:         246
        .size:           2
        .value_kind:     hidden_remainder_z
      - .offset:         264
        .size:           8
        .value_kind:     hidden_global_offset_x
      - .offset:         272
        .size:           8
        .value_kind:     hidden_global_offset_y
      - .offset:         280
        .size:           8
        .value_kind:     hidden_global_offset_z
      - .offset:         288
        .size:           2
        .value_kind:     hidden_grid_dims
      - .offset:         312
        .size:           8
        .value_kind:     hidden_multigrid_sync_arg
      - .offset:         344
        .size:           4
        .value_kind:     hidden_dynamic_lds_size
    .group_segment_fixed_size: 0
    .kernarg_segment_align: 8
    .kernarg_segment_size: 480
    .language:       OpenCL C
    .language_version:
      - 2
      - 0
    .max_flat_workgroup_size: 512
    .name:           _Z4mega4Args
    .private_segment_fixed_size: 0
    .sgpr_count:     106
    .sgpr_spill_count: 45
    .symbol:         _Z4mega4Args.kd
    .uniform_work_group_size: 1
    .uses_dynamic_stack: false
    .vgpr_count:     256
    .vgpr_spill_count: 0
    .wavefront_size: 64
